# hgrn1 readout: output-gate and norm-gain loads hoisted above the last MFMA block instead of load-then-wait (epilogue de-serialisation)
# baseline (speedup 1.0000x reference)
; #define LAS __attribute__((address_space(3)))
; DI float shx_(int lane, float v, int m) { return __builtin_bit_cast(float, __builtin_amdgcn_ds_bpermute((lane ^ m) << 2, __builtin_bit_cast(int, v))); }
; DI float silu_f(float x) { return x / (1.f + __expf(-x)); }
; #define MFMA32(a, b, c) __builtin_amdgcn_mfma_f32_32x32x16_bf16((a), (b), (c), 0, 0, 0)
; template <int MODE> DI void hgrn_chunk_phase(const Args& A, int wave_s, int l, bool need_ctx, LAS unsigned char* lds) {
;     ...
; #pragma unroll
;             for (int ks = 0; ks < 4; ++ks) { const bf16x8 a = tr_nat(SP, 16 * ks, 32 * mt, lane), bq = *(LAS bf16x8*)(QQ + (32 * tblk + r) * KV_PITCH + ks * 32 + h5 * 16); O = MFMA32(a, bq, O); }
;             const int pos = 32 * tblk + r, tloc = dir ? 63 - pos : pos;
; #pragma unroll
;             for (int i = 0; i < 16; ++i) { const int dv = 32 * mt + (i & 3) + 8 * (i >> 2) + 4 * h5; OX[(dir * 64 + tloc) * 68 + dv] = O[i]; }
;             __syncthreads();
;             {
;                 const int t = C.tid >> 3, part = C.tid & 7; const int row = rbase + t;
;                 float tot[8]; float ss = 0.f;
; #pragma unroll
;                 for (int e = 0; e < 8; ++e) { tot[e] = OX[t * 68 + part * 8 + e] + OX[(64 + t) * 68 + part * 8 + e]; ss += tot[e] * tot[e]; }
;                 ss += shx_(C.lane, ss, 1); ss += shx_(C.lane, ss, 2); ss += shx_(C.lane, ss, 4);
;                 const float rs = rsqrtf(ss * (1.f / 64.f) + EPS);
;                 const v4u gr = *(const v4u*)(C.P + (size_t)row * INW + CB_G + hd * 64 + part * 8);
;     ...
;                     const float y0 = tot[2 * q] * rs * C.hgog[l * 64 + part * 8 + 2 * q] * silu_f(g0), y1 = tot[2 * q + 1] * rs * C.hgog[l * 64 + part * 8 + 2 * q + 1] * silu_f(g1);
.LBB0_383:
	v_add_u32_e32 v130, s96, v61
	s_lshl_b32 s60, s58, 1
	s_mov_b32 s61, 0
	v_mov_b64_e32 v[128:129], s[84:85]
	v_mad_i64_i32 v[128:129], s[54:55], v130, s77, v[128:129]
	v_lshl_add_u64 v[128:129], v[128:129], 0, s[60:61]
	v_lshl_add_u64 v[128:129], v[128:129], 0, v[160:161]
	v_add_co_u32_e32 v128, vcc, s76, v128
	s_nop 1
	v_addc_co_u32_e32 v129, vcc, 0, v129, vcc
	global_load_dwordx4 v[132:135], v[128:129], off
	global_load_dwordx4 v[136:139], v[44:45], off offset:16
	global_load_dwordx4 v[140:143], v[44:45], off
	ds_read_b64_tr_b16 v[16:17], v70 offset:36864
	ds_read_b64_tr_b16 v[18:19], v70 offset:37440
	ds_read_b128 v[20:23], v72 offset:18432
	ds_read_b128 v[24:27], v72 offset:18464
	s_add_i32 s83, s83, s92
	s_sub_i32 s2, s2, s90
	v_mov_b32_e32 v43, v79
	s_waitcnt lgkmcnt(1)
	v_mfma_f32_32x32x16_bf16 v[0:15], v[16:19], v[20:23], v[0:15]
	ds_read_b64_tr_b16 v[16:17], v70 offset:39168
	ds_read_b64_tr_b16 v[18:19], v70 offset:39744
	v_mov_b32_e32 v41, v80
	v_mov_b32_e32 v40, v85
	v_mov_b32_e32 v42, v76
	v_mov_b32_e32 v106, v92
	s_mov_b32 s59, s95
	v_readlane_b32 s95, v255, 24
	s_waitcnt lgkmcnt(0)
	v_mfma_f32_32x32x16_bf16 v[0:15], v[16:19], v[24:27], v[0:15]
	ds_read_b64_tr_b16 v[16:17], v70 offset:41472
	ds_read_b64_tr_b16 v[18:19], v70 offset:42048
	ds_read_b128 v[20:23], v72 offset:18496
	s_waitcnt lgkmcnt(0)
	v_mfma_f32_32x32x16_bf16 v[0:15], v[16:19], v[20:23], v[0:15]
	ds_read_b64_tr_b16 v[16:17], v70 offset:43776
	ds_read_b64_tr_b16 v[18:19], v70 offset:44352
	ds_read_b128 v[20:23], v72 offset:18528
	s_waitcnt lgkmcnt(0)
	v_mfma_f32_32x32x16_bf16 v[0:15], v[16:19], v[20:23], v[0:15]
	v_add_u32_e32 v16, s96, v61
	s_lshl_b32 s96, s58, 1
	v_ashrrev_i32_e32 v17, 31, v16
	s_nop 8
	ds_write_b128 v66, v[0:3]
	ds_write_b128 v66, v[4:7] offset:32
	ds_write_b128 v66, v[8:11] offset:64
	ds_write_b128 v66, v[12:15] offset:96
	v_mov_b64_e32 v[0:1], s[84:85]
	v_mad_i64_i32 v[0:1], s[54:55], v16, s77, v[0:1]
	v_lshl_add_u64 v[0:1], v[0:1], 0, s[96:97]
	v_lshl_add_u64 v[0:1], v[0:1], 0, v[160:161]
	v_add_co_u32_e32 v0, vcc, s76, v0
	s_waitcnt lgkmcnt(0)
	s_nop 0
	v_addc_co_u32_e32 v1, vcc, 0, v1, vcc
	s_barrier
; DI float shx_(int lane, float v, int m) { return __builtin_bit_cast(float, __builtin_amdgcn_ds_bpermute((lane ^ m) << 2, __builtin_bit_cast(int, v))); }
; DI float silu_f(float x) { return x / (1.f + __expf(-x)); }
; DI unsigned pkbf(float a, float b) { fv2 v = {a, b}; return __builtin_bit_cast(unsigned, __builtin_convertvector(v, bfv2)); }
; template <int MODE> DI void hgrn_chunk_phase(const Args& A, int wave_s, int l, bool need_ctx, LAS unsigned char* lds) {
;     ...
;             {
;                 const int t = C.tid >> 3, part = C.tid & 7; const int row = rbase + t;
;                 float tot[8]; float ss = 0.f;
; #pragma unroll
;                 for (int e = 0; e < 8; ++e) { tot[e] = OX[t * 68 + part * 8 + e] + OX[(64 + t) * 68 + part * 8 + e]; ss += tot[e] * tot[e]; }
;                 ss += shx_(C.lane, ss, 1); ss += shx_(C.lane, ss, 2); ss += shx_(C.lane, ss, 4);
;                 const float rs = rsqrtf(ss * (1.f / 64.f) + EPS);
;                 const v4u gr = *(const v4u*)(C.P + (size_t)row * INW + CB_G + hd * 64 + part * 8);
;                 unsigned res[4];
; #pragma unroll
;                 for (int q = 0; q < 4; ++q) { const float g0 = __builtin_bit_cast(float, gr[q] << 16), g1 = __builtin_bit_cast(float, gr[q] & 0xffff0000u);
;                     const float y0 = tot[2 * q] * rs * C.hgog[l * 64 + part * 8 + 2 * q] * silu_f(g0), y1 = tot[2 * q + 1] * rs * C.hgog[l * 64 + part * 8 + 2 * q + 1] * silu_f(g1);
;                     res[q] = pkbf(y0, y1); }
;                 v4u o; o.x = res[0]; o.y = res[1]; o.z = res[2]; o.w = res[3];
;                 *(v4u*)(C.MIX + (size_t)row * 1024 + 512 + hd * 64 + part * 8) = o;
	s_nop 0
	ds_read_b128 v[12:15], v62
	ds_read_b128 v[4:7], v62 offset:16
	ds_read_b128 v[8:11], v62 offset:17424
	s_waitcnt lgkmcnt(0)
	v_pk_add_f32 v[20:21], v[4:5], v[8:9]
	v_pk_add_f32 v[18:19], v[6:7], v[10:11]
	v_pk_mul_f32 v[26:27], v[20:21], v[20:21]
	v_pk_mul_f32 v[24:25], v[18:19], v[18:19]
	s_waitcnt vmcnt(0)
	v_mov_b32_e32 v0, v132
	v_mov_b32_e32 v1, v133
	v_mov_b32_e32 v2, v134
	v_mov_b32_e32 v3, v135
	v_lshlrev_b32_e32 v28, 16, v2
	v_and_b32_e32 v2, 0xffff0000, v2
	v_mul_f32_e32 v4, 0xbfb8aa3b, v28
	v_mul_f32_e32 v23, 0xbfb8aa3b, v2
	v_exp_f32_e32 v22, v4
	v_exp_f32_e32 v23, v23
	v_mov_b32_e32 v4, v136
	v_mov_b32_e32 v5, v137
	v_mov_b32_e32 v6, v138
	v_mov_b32_e32 v7, v139
	v_mov_b32_e32 v8, v140
	v_mov_b32_e32 v9, v141
	v_mov_b32_e32 v10, v142
	v_mov_b32_e32 v11, v143
	v_pk_add_f32 v[22:23], v[22:23], 1.0 op_sel_hi:[1,0]
	s_nop 0
	v_div_scale_f32 v29, s[54:55], v23, v23, v2
	v_rcp_f32_e32 v30, v29
	s_nop 0
	v_fma_f32 v31, -v29, v30, 1.0
	v_fmac_f32_e32 v30, v31, v30
	v_div_scale_f32 v31, vcc, v2, v23, v2
	v_mul_f32_e32 v32, v31, v30
	v_fma_f32 v33, -v29, v32, v31
	v_fmac_f32_e32 v32, v33, v30
	v_fma_f32 v29, -v29, v32, v31
	v_div_fmas_f32 v29, v29, v30, v32
	v_div_fixup_f32 v23, v29, v23, v2
	v_div_scale_f32 v2, s[54:55], v22, v22, v28
	v_rcp_f32_e32 v29, v2
	s_nop 0
	v_fma_f32 v30, -v2, v29, 1.0
	v_fmac_f32_e32 v29, v30, v29
	v_div_scale_f32 v30, vcc, v28, v22, v28
	v_mul_f32_e32 v31, v30, v29
	v_fma_f32 v32, -v2, v31, v30
	v_fmac_f32_e32 v31, v32, v29
	v_fma_f32 v2, -v2, v31, v30
	v_div_fmas_f32 v2, v2, v29, v31
	v_div_fixup_f32 v22, v2, v22, v28
	v_lshlrev_b32_e32 v2, 16, v1
	v_and_b32_e32 v1, 0xffff0000, v1
	v_mul_f32_e32 v28, 0xbfb8aa3b, v2
	v_mul_f32_e32 v29, 0xbfb8aa3b, v1
	ds_read_b128 v[32:35], v62 offset:17408
	v_exp_f32_e32 v28, v28
	v_exp_f32_e32 v29, v29
	s_waitcnt lgkmcnt(0)
	v_pk_add_f32 v[14:15], v[14:15], v[34:35]
	v_pk_add_f32 v[28:29], v[28:29], 1.0 op_sel_hi:[1,0]
	v_pk_add_f32 v[12:13], v[12:13], v[32:33]
	v_div_scale_f32 v34, s[54:55], v29, v29, v1
	v_rcp_f32_e32 v35, v34
	v_pk_mul_f32 v[32:33], v[12:13], v[12:13]
	v_pk_mul_f32 v[30:31], v[14:15], v[14:15]
	v_fma_f32 v36, -v34, v35, 1.0
	v_fmac_f32_e32 v35, v36, v35
	v_div_scale_f32 v36, vcc, v1, v29, v1
	v_mul_f32_e32 v37, v36, v35
	v_fma_f32 v38, -v34, v37, v36
	v_fmac_f32_e32 v37, v38, v35
	v_fma_f32 v34, -v34, v37, v36
	v_div_fmas_f32 v34, v34, v35, v37
	v_div_fixup_f32 v29, v34, v29, v1
	v_div_scale_f32 v1, s[54:55], v28, v28, v2
	v_rcp_f32_e32 v34, v1
	s_nop 0
	v_fma_f32 v35, -v1, v34, 1.0
	v_fmac_f32_e32 v34, v35, v34
	v_div_scale_f32 v35, vcc, v2, v28, v2
	v_mul_f32_e32 v36, v35, v34
	v_fma_f32 v37, -v1, v36, v35
	v_fmac_f32_e32 v36, v37, v34
	v_fma_f32 v1, -v1, v36, v35
	v_div_fmas_f32 v1, v1, v34, v36
	v_div_fixup_f32 v28, v1, v28, v2
	v_lshlrev_b32_e32 v2, 16, v0
	v_and_b32_e32 v34, 0xffff0000, v0
	v_mul_f32_e32 v0, 0xbfb8aa3b, v2
	v_mul_f32_e32 v1, 0xbfb8aa3b, v34
	v_exp_f32_e32 v0, v0
	v_exp_f32_e32 v1, v1
	s_nop 0
	v_pk_add_f32 v[0:1], v[0:1], 1.0 op_sel_hi:[1,0]
	s_nop 0
	v_div_scale_f32 v35, s[54:55], v1, v1, v34
	v_rcp_f32_e32 v36, v35
	s_nop 0
	v_fma_f32 v37, -v35, v36, 1.0
	v_fmac_f32_e32 v36, v37, v36
	v_div_scale_f32 v37, vcc, v34, v1, v34
	v_mul_f32_e32 v38, v37, v36
	v_fma_f32 v39, -v35, v38, v37
	v_fmac_f32_e32 v38, v39, v36
	v_fma_f32 v35, -v35, v38, v37
	v_div_fmas_f32 v35, v35, v36, v38
	v_div_fixup_f32 v1, v35, v1, v34
	v_div_scale_f32 v34, s[54:55], v0, v0, v2
	v_rcp_f32_e32 v35, v34
	v_mov_b32_e32 v39, v78
	v_fma_f32 v36, -v34, v35, 1.0
	v_fmac_f32_e32 v35, v36, v35
	v_div_scale_f32 v36, vcc, v2, v0, v2
	v_mul_f32_e32 v37, v36, v35
	v_fma_f32 v38, -v34, v37, v36
	v_fmac_f32_e32 v37, v38, v35
	v_fma_f32 v34, -v34, v37, v36
	v_div_fmas_f32 v34, v34, v35, v37
	v_div_fixup_f32 v0, v34, v0, v2
	v_add_f32_e32 v2, v32, v33
	v_add_f32_e32 v2, v2, v30
	v_add_f32_e32 v2, v2, v31
	v_add_f32_e32 v2, v2, v26
	v_add_f32_e32 v2, v2, v27
	v_add_f32_e32 v2, v2, v24
	v_add_f32_e32 v2, v2, v25
	ds_bpermute_b32 v24, v63, v2
	v_mov_b32_e32 v27, v105
	v_mov_b32_e32 v26, v103
	v_mov_b32_e32 v37, v87
	v_mov_b32_e32 v36, v89
	s_waitcnt lgkmcnt(0)
	v_add_f32_e32 v2, v2, v24
	ds_bpermute_b32 v24, v64, v2
	v_mov_b32_e32 v33, v94
	v_mov_b32_e32 v32, v96
	v_mov_b32_e32 v38, v82
	v_mov_b32_e32 v35, v84
	s_waitcnt lgkmcnt(0)
	v_add_f32_e32 v2, v2, v24
	ds_bpermute_b32 v24, v65, v2
	v_mov_b32_e32 v34, v86
	v_mov_b32_e32 v31, v91
	v_mov_b32_e32 v30, v93
	s_waitcnt lgkmcnt(0)
	v_add_f32_e32 v2, v2, v24
	v_fmamk_f32 v2, v2, 0x3c800000, v162
	v_cmp_gt_f32_e32 vcc, s78, v2
	v_mul_f32_e32 v24, 0x4b800000, v2
	s_nop 0
	v_cndmask_b32_e32 v2, v2, v24, vcc
	v_rsq_f32_e32 v2, v2
	s_nop 0
	v_mul_f32_e32 v24, 0x45800000, v2
	v_cndmask_b32_e32 v24, v2, v24, vcc
	v_pk_mul_f32 v[12:13], v[12:13], v[24:25] op_sel_hi:[1,0]
	s_waitcnt vmcnt(0)
	v_pk_mul_f32 v[8:9], v[8:9], v[12:13]
	s_nop 0
	v_pk_mul_f32 v[0:1], v[0:1], v[8:9]
	v_pk_mul_f32 v[8:9], v[14:15], v[24:25] op_sel_hi:[1,0]
	v_cvt_pk_bf16_f32 v0, v0, v1
	v_pk_mul_f32 v[8:9], v[10:11], v[8:9]
	v_lshlrev_b32_e32 v10, 16, v3
	v_pk_mul_f32 v[8:9], v[28:29], v[8:9]
	v_and_b32_e32 v3, 0xffff0000, v3
	v_cvt_pk_bf16_f32 v1, v8, v9
	v_pk_mul_f32 v[8:9], v[20:21], v[24:25] op_sel_hi:[1,0]
	v_mov_b32_e32 v21, v100
	v_pk_mul_f32 v[4:5], v[4:5], v[8:9]
	v_pk_mul_f32 v[8:9], v[18:19], v[24:25] op_sel_hi:[1,0]
	v_pk_mul_f32 v[4:5], v[22:23], v[4:5]
	v_pk_mul_f32 v[6:7], v[6:7], v[8:9]
	v_cvt_pk_bf16_f32 v2, v4, v5
	v_mul_f32_e32 v4, 0xbfb8aa3b, v10
	v_mul_f32_e32 v5, 0xbfb8aa3b, v3
	v_exp_f32_e32 v4, v4
	v_exp_f32_e32 v5, v5
	v_mov_b32_e32 v25, v104
	v_mov_b32_e32 v23, v102
	v_mov_b32_e32 v24, v101
	v_pk_add_f32 v[4:5], v[4:5], 1.0 op_sel_hi:[1,0]
	v_mov_b32_e32 v22, v99
	v_div_scale_f32 v8, s[54:55], v5, v5, v3
	v_rcp_f32_e32 v9, v8
	v_mov_b32_e32 v20, v98
	v_mov_b32_e32 v29, v97
	v_mov_b32_e32 v28, v95
	v_fma_f32 v11, -v8, v9, 1.0
	v_fmac_f32_e32 v9, v11, v9
	v_div_scale_f32 v11, vcc, v3, v5, v3
	v_mul_f32_e32 v12, v11, v9
	v_fma_f32 v13, -v8, v12, v11
	v_fmac_f32_e32 v12, v13, v9
	v_fma_f32 v8, -v8, v12, v11
	v_div_fmas_f32 v8, v8, v9, v12
	v_div_fixup_f32 v5, v8, v5, v3
	v_div_scale_f32 v3, s[54:55], v4, v4, v10
	v_rcp_f32_e32 v8, v3
	s_nop 0
	v_fma_f32 v9, -v3, v8, 1.0
	v_fmac_f32_e32 v8, v9, v8
	v_div_scale_f32 v9, vcc, v10, v4, v10
	v_mul_f32_e32 v11, v9, v8
	v_fma_f32 v12, -v3, v11, v9
	v_fmac_f32_e32 v11, v12, v8
	v_fma_f32 v3, -v3, v11, v9
	v_div_fmas_f32 v3, v3, v8, v11
	v_div_fixup_f32 v4, v3, v4, v10
	v_pk_mul_f32 v[4:5], v[4:5], v[6:7]
	v_mov_b32_e32 v6, v77
	v_cvt_pk_bf16_f32 v3, v4, v5
	v_lshlrev_b64 v[4:5], 11, v[16:17]
	v_lshl_add_u64 v[4:5], s[88:89], 0, v[4:5]
	v_lshl_add_u64 v[4:5], v[4:5], 0, s[96:97]
	v_lshl_add_u64 v[4:5], v[4:5], 0, v[160:161]
	v_add_co_u32_e32 v4, vcc, 0x7a00000, v4
	v_mov_b32_e32 v8, v81
	s_nop 0
	v_addc_co_u32_e32 v5, vcc, 0, v5, vcc
	global_store_dwordx4 v[4:5], v[0:3], off offset:1024
	s_andn2_b64 vcc, exec, s[74:75]
	v_mov_b32_e32 v4, v75
	v_mov_b32_e32 v2, v74
	v_mov_b32_e32 v12, v83
	v_mov_b32_e32 v11, v88
	v_mov_b32_e32 v10, v90
	s_cbranch_vccz .LBB0_398
